# S.next division by constant group size 8 replaced by shift/and in up-GEMM unit loop
# baseline (speedup 1.0000x reference)
;     __host__ __device__ bool next(int i, Unit& u) const {
;         const long L = (long)i * G + c; if (L >= nwg) return false;
;         int wgid = (int)L; { const int q = nwg / NXCD, r = nwg % NXCD, xcd = wgid % NXCD, off = wgid / NXCD; wgid = (xcd < r ? xcd * (q + 1) : r * (q + 1) + (xcd - r) * q) + off; }
;         const int nig = WGM * nN, gid = wgid / nig, fm = gid * WGM, gsz = (nM - fm) < WGM ? (nM - fm) : WGM;
;         u.pm = fm + ((wgid % nig) % gsz); u.pn = (wgid % nig) / gsz; u.pb = 0; return true;
.LBB0_1209:
	s_add_i32 s59, s59, 1
	s_mul_i32 s19, s59, s33
	s_mul_hi_u32 s20, s59, s50
	s_add_i32 s20, s20, s19
	s_mul_i32 s19, s59, s50
	s_add_u32 s30, s19, s2
	s_addc_u32 s31, s20, s3
	v_mov_b64_e32 v[2:3], 0x1600
	v_cmp_lt_i64_e64 s[42:43], s[30:31], v[2:3]
	v_mov_b64_e32 v[2:3], 0x15ff
	v_cmp_gt_i64_e32 vcc, s[30:31], v[2:3]
	s_cbranch_vccnz .LBB0_1211
	s_ashr_i32 s18, s30, 31
	s_lshr_b32 s18, s18, 29
	s_add_i32 s18, s30, s18
	s_ashr_i32 s19, s18, 3
	s_and_b32 s18, s18, -8
	s_sub_i32 s18, s30, s18
	s_cmp_lt_i32 s18, 0
	s_movk_i32 s20, 0x2c1
	s_cselect_b32 s20, s20, 0x2c0
	s_mul_i32 s18, s18, s20
	s_add_i32 s18, s18, s19
	s_mul_hi_i32 s19, s18, 0x2e8ba2e9
	s_lshr_b32 s20, s19, 31
	s_ashr_i32 s19, s19, 5
	s_add_i32 s19, s19, s20
	s_lshl_b32 s20, s19, 3
	s_mulk_i32 s19, 0xb0
	s_sub_i32 s19, s18, s19
	s_lshr_b32 s18, s19, 3
	s_and_b32 s19, s19, 7
	s_add_i32 s28, s20, s19
